# compression hand-off: workgroup-scope sync only (dropped agent-scope wbl2/inv between EpiCmp1 and cmp_gemm2, same-CU producer/consumer)
# baseline (speedup 1.0000x reference)
; #define LAUNDER(x) asm volatile("" : "+v"(x))
; #define MFMA32(a, b, c) __builtin_amdgcn_mfma_f32_32x32x16_bf16((a), (b), (c), 0, 0, 0)
; #define WAVE_F (__builtin_amdgcn_readfirstlane(TID_F >> 6))
; __device__ __forceinline__ void cmp_gemm2(const bf16_t* hidden, const bf16_t* w2t, bf16_t* kcmp, bf16_t* vcmpT, int kv, int row0, int lane) {
;     LAUNDER(lane);
;     const int r = lane & 31, h = lane >> 5;
;     f32x16 acc[2];
; #pragma unroll
;     for (int i = 0; i < 16; ++i) { acc[0][i] = 0.f; acc[1][i] = 0.f; }
; #pragma unroll
;     for (int ks = 0; ks < 16; ++ks) {
;         const bf16x8 hf = *(const bf16x8*)(hidden + (size_t)(row0 + r) * 256 + ks * 16 + h * 8);
; #pragma unroll
;         for (int dt = 0; dt < 2; ++dt) {
;             const bf16x8 wf = *(const bf16x8*)(w2t + (size_t)(dt * 32 + r) * 256 + ks * 16 + h * 8);
;             if (kv == 0) acc[dt] = MFMA32(wf, hf, acc[dt]);
;             else         acc[dt] = MFMA32(hf, wf, acc[dt]);
;         }
;     }
; __global__ void __launch_bounds__(NTHREADS, 2) fwd_megakernel(Params p) {
;     ...
;                     asm volatile("s_waitcnt vmcnt(0)" ::: "memory");
;                     __builtin_amdgcn_fence(__ATOMIC_RELEASE, "agent");
;                     __syncthreads();
;                     __builtin_amdgcn_fence(__ATOMIC_ACQUIRE, "agent");
;                     cmp_gemm2(hid, (const bf16_t*)(wl + (kv ? W_C2V : W_C2K)), (bf16_t*)(ws + WS_R1 + R_KCMP), (bf16_t*)(ws + WS_R1 + R_VCMPT), kv, u.pm * 256 + WAVE_F * 32, LANE_F);
.LBB0_529:
	s_and_b64 s[4:5], exec, s[4:5]
	s_mov_b32 s4, 0x1980000
	v_mov_b32_e32 v1, v222
	s_waitcnt vmcnt(0)
	s_waitcnt vmcnt(0)
	s_barrier
	s_cselect_b32 s4, s4, 0x1990000
	s_add_u32 s4, s36, s4
	v_readfirstlane_b32 s11, v1
	v_mov_b32_e32 v1, v222
	s_addc_u32 s5, s37, 0
	v_readlane_b32 s10, v252, 5
	s_ashr_i32 s11, s11, 1
	s_lshl_b32 s10, s10, 8
	s_andn2_b32 s11, s11, 31
	v_and_b32_e32 v1, 63, v1
	s_add_i32 s10, s11, s10
	s_and_b64 vcc, exec, s[6:7]
	v_and_b32_e32 v76, 31, v1
	v_ashrrev_i32_e32 v1, 5, v1
	v_or_b32_e32 v2, s10, v76
	v_ashrrev_i32_e32 v3, 31, v2
	v_lshlrev_b32_e32 v4, 3, v1
	v_lshlrev_b64 v[2:3], 9, v[2:3]
	v_ashrrev_i32_e32 v5, 31, v4
	v_lshl_add_u64 v[2:3], s[8:9], 0, v[2:3]
	v_lshlrev_b64 v[4:5], 1, v[4:5]
	v_lshl_add_u64 v[66:67], v[2:3], 0, v[4:5]
	v_lshl_add_u64 v[70:71], s[4:5], 0, v[4:5]
	v_lshlrev_b32_e32 v2, 9, v76
	v_mov_b32_e32 v3, v0
	v_lshl_add_u64 v[72:73], v[70:71], 0, v[2:3]
	v_lshlrev_b32_e32 v18, 8, v76
	v_or_b32_e32 v18, 0x2000, v18
	v_lshlrev_b32_e32 v74, 1, v18
	v_mov_b32_e32 v75, v0
	v_lshl_add_u64 v[68:69], v[70:71], 0, v[74:75]
	s_andn2_b64 s[4:5], exec, s[6:7]
	global_load_dwordx4 v[80:83], v[66:67], off
	global_load_dwordx4 v[144:147], v[72:73], off
	global_load_dwordx4 v[34:37], v[68:69], off
	global_load_dwordx4 v[84:87], v[66:67], off offset:32
	global_load_dwordx4 v[148:151], v[72:73], off offset:32
	global_load_dwordx4 v[38:41], v[68:69], off offset:32
	global_load_dwordx4 v[88:91], v[66:67], off offset:64
	global_load_dwordx4 v[152:155], v[72:73], off offset:64
	global_load_dwordx4 v[42:45], v[68:69], off offset:64
	global_load_dwordx4 v[92:95], v[66:67], off offset:96
	global_load_dwordx4 v[156:159], v[72:73], off offset:96
	global_load_dwordx4 v[46:49], v[68:69], off offset:96
	global_load_dwordx4 v[96:99], v[66:67], off offset:128
	global_load_dwordx4 v[160:163], v[72:73], off offset:128
	global_load_dwordx4 v[50:53], v[68:69], off offset:128
	global_load_dwordx4 v[100:103], v[66:67], off offset:160
	global_load_dwordx4 v[164:167], v[72:73], off offset:160
	global_load_dwordx4 v[54:57], v[68:69], off offset:160
	global_load_dwordx4 v[104:107], v[66:67], off offset:192
	global_load_dwordx4 v[168:171], v[72:73], off offset:192
	global_load_dwordx4 v[58:61], v[68:69], off offset:192
	global_load_dwordx4 v[108:111], v[66:67], off offset:224
	global_load_dwordx4 v[172:175], v[72:73], off offset:224
	global_load_dwordx4 v[62:65], v[68:69], off offset:224
	global_load_dwordx4 v[112:115], v[66:67], off offset:256
	global_load_dwordx4 v[176:179], v[72:73], off offset:256
	global_load_dwordx4 v[116:119], v[66:67], off offset:288
	global_load_dwordx4 v[184:187], v[72:73], off offset:288
	global_load_dwordx4 v[120:123], v[66:67], off offset:320
	global_load_dwordx4 v[188:191], v[72:73], off offset:320
	global_load_dwordx4 v[124:127], v[66:67], off offset:352
	global_load_dwordx4 v[192:195], v[72:73], off offset:352
	global_load_dwordx4 v[128:131], v[66:67], off offset:384
	global_load_dwordx4 v[196:199], v[72:73], off offset:384
	global_load_dwordx4 v[132:135], v[66:67], off offset:416
	global_load_dwordx4 v[200:203], v[72:73], off offset:416
	global_load_dwordx4 v[136:139], v[66:67], off offset:448
	global_load_dwordx4 v[204:207], v[72:73], off offset:448
	global_load_dwordx4 v[140:143], v[66:67], off offset:480
	global_load_dwordx4 v[208:211], v[72:73], off offset:480
	s_and_b64 vcc, exec, s[6:7]
	s_cbranch_vccz .Lc2_kv0
	s_waitcnt vmcnt(37)
	v_mfma_f32_32x32x16_bf16 v[18:33], v[80:83], v[144:147], 0
	v_mfma_f32_32x32x16_bf16 v[2:17], v[80:83], v[34:37], 0
	s_waitcnt vmcnt(34)
	v_mfma_f32_32x32x16_bf16 v[18:33], v[84:87], v[148:151], v[18:33]
	v_mfma_f32_32x32x16_bf16 v[2:17], v[84:87], v[38:41], v[2:17]
	s_waitcnt vmcnt(31)
	v_mfma_f32_32x32x16_bf16 v[18:33], v[88:91], v[152:155], v[18:33]
	v_mfma_f32_32x32x16_bf16 v[2:17], v[88:91], v[42:45], v[2:17]
	s_waitcnt vmcnt(28)
	v_mfma_f32_32x32x16_bf16 v[18:33], v[92:95], v[156:159], v[18:33]
	v_mfma_f32_32x32x16_bf16 v[2:17], v[92:95], v[46:49], v[2:17]
	s_waitcnt vmcnt(25)
	v_mfma_f32_32x32x16_bf16 v[18:33], v[96:99], v[160:163], v[18:33]
	v_mfma_f32_32x32x16_bf16 v[2:17], v[96:99], v[50:53], v[2:17]
	s_waitcnt vmcnt(22)
	v_mfma_f32_32x32x16_bf16 v[18:33], v[100:103], v[164:167], v[18:33]
	v_mfma_f32_32x32x16_bf16 v[2:17], v[100:103], v[54:57], v[2:17]
	s_waitcnt vmcnt(19)
	v_mfma_f32_32x32x16_bf16 v[18:33], v[104:107], v[168:171], v[18:33]
	v_mfma_f32_32x32x16_bf16 v[2:17], v[104:107], v[58:61], v[2:17]
	s_waitcnt vmcnt(16)
	v_mfma_f32_32x32x16_bf16 v[18:33], v[108:111], v[172:175], v[18:33]
	v_mfma_f32_32x32x16_bf16 v[2:17], v[108:111], v[62:65], v[2:17]
	global_load_dwordx4 v[144:147], v[68:69], off offset:256
	global_load_dwordx4 v[148:151], v[68:69], off offset:288
	global_load_dwordx4 v[152:155], v[68:69], off offset:320
	global_load_dwordx4 v[156:159], v[68:69], off offset:352
	global_load_dwordx4 v[160:163], v[68:69], off offset:384
	global_load_dwordx4 v[164:167], v[68:69], off offset:416
	global_load_dwordx4 v[168:171], v[68:69], off offset:448
	global_load_dwordx4 v[172:175], v[68:69], off offset:480
	s_waitcnt vmcnt(22)
	v_mfma_f32_32x32x16_bf16 v[18:33], v[112:115], v[176:179], v[18:33]
	s_waitcnt vmcnt(20)
	v_mfma_f32_32x32x16_bf16 v[18:33], v[116:119], v[184:187], v[18:33]
	s_waitcnt vmcnt(18)
	v_mfma_f32_32x32x16_bf16 v[18:33], v[120:123], v[188:191], v[18:33]
	s_waitcnt vmcnt(16)
	v_mfma_f32_32x32x16_bf16 v[18:33], v[124:127], v[192:195], v[18:33]
	s_waitcnt vmcnt(14)
	v_mfma_f32_32x32x16_bf16 v[18:33], v[128:131], v[196:199], v[18:33]
	s_waitcnt vmcnt(12)
	v_mfma_f32_32x32x16_bf16 v[18:33], v[132:135], v[200:203], v[18:33]
	s_waitcnt vmcnt(10)
	v_mfma_f32_32x32x16_bf16 v[18:33], v[136:139], v[204:207], v[18:33]
	s_waitcnt vmcnt(8)
	v_mfma_f32_32x32x16_bf16 v[18:33], v[140:143], v[208:211], v[18:33]
	s_waitcnt vmcnt(7)
	v_mfma_f32_32x32x16_bf16 v[2:17], v[112:115], v[144:147], v[2:17]
	s_waitcnt vmcnt(6)
	v_mfma_f32_32x32x16_bf16 v[2:17], v[116:119], v[148:151], v[2:17]
	s_waitcnt vmcnt(5)
	v_mfma_f32_32x32x16_bf16 v[2:17], v[120:123], v[152:155], v[2:17]
	s_waitcnt vmcnt(4)
	v_mfma_f32_32x32x16_bf16 v[2:17], v[124:127], v[156:159], v[2:17]
	s_waitcnt vmcnt(3)
	v_mfma_f32_32x32x16_bf16 v[2:17], v[128:131], v[160:163], v[2:17]
	s_waitcnt vmcnt(2)
	v_mfma_f32_32x32x16_bf16 v[2:17], v[132:135], v[164:167], v[2:17]
	s_waitcnt vmcnt(1)
	v_mfma_f32_32x32x16_bf16 v[2:17], v[136:139], v[168:171], v[2:17]
	s_waitcnt vmcnt(0)
	v_mfma_f32_32x32x16_bf16 v[2:17], v[140:143], v[172:175], v[2:17]
	s_branch .LBB0_657
